# GU tail spread over the six fastest bid%8 groups x 16 workgroups each (instead of three whole groups), steps 1-2; step 0 static
# baseline (speedup 1.0000x reference)
.LBB0_840:
	s_add_u32 s6, s6, 0xac00000
	s_addc_u32 s7, s7, 0
	v_and_b32_e32 v17, 15, v16
	v_lshrrev_b32_e32 v18, 1, v16
	s_lshl_b32 s2, s2, 5
	v_and_b32_e32 v18, 24, v18
	v_lshlrev_b32_e32 v19, 6, v17
	v_lshlrev_b32_e32 v16, 2, v16
	s_and_b32 s22, s2, 0x60
	s_add_i32 m0, s46, 0x18000
	v_lshl_add_u64 v[8:9], v[8:9], 0, s[70:71]
	v_lshl_or_b32 v19, v18, 1, v19
	v_and_b32_e32 v16, 32, v16
	v_lshl_or_b32 v144, s3, 6, v17
	s_lshl_b32 s3, s3, 13
	s_lshl_b32 s2, s22, 7
	s_waitcnt vmcnt(2)
	s_barrier
	global_load_lds_dwordx4 v[8:9], off
	v_lshl_add_u64 v[6:7], v[6:7], 0, s[70:71]
	s_add_i32 m0, s46, 0x1a000
	s_add_i32 s50, s46, 0x8000
	s_add_i32 s51, s46, 0xa000
	v_bitop3_b32 v145, s2, v19, v16 bitop3:0xf6
	global_load_lds_dwordx4 v[6:7], off
	v_lshl_add_u64 v[2:3], v[2:3], 0, s[70:71]
	s_mov_b32 m0, s50
	s_add_u32 s2, s38, 0x40080
	v_bitop3_b32 v17, v19, s3, v16 bitop3:0xde
	global_load_lds_dwordx4 v[2:3], off
	v_lshl_add_u64 v[2:3], v[4:5], 0, s[70:71]
	s_mov_b32 m0, s51
	s_addc_u32 s3, s39, 0
	global_load_lds_dwordx4 v[2:3], off
	s_add_i32 m0, s46, 0x1c000
	v_lshl_add_u64 v[2:3], s[2:3], 0, v[0:1]
	global_load_lds_dwordx4 v[2:3], off
	v_lshl_add_u64 v[2:3], s[2:3], 0, v[134:135]
	s_add_i32 m0, s46, 0x1e000
	s_cmpk_lt_u32 s9, 0x100
	global_load_lds_dwordx4 v[2:3], off
	v_lshlrev_b32_e32 v2, 14, v10
	v_and_b32_e32 v2, 0xffff8000, v2
	v_lshl_add_u32 v2, v11, 11, v2
	v_and_b32_e32 v3, 1, v10
	v_lshl_or_b32 v2, v3, 6, v2
	v_lshl_add_u32 v136, v12, 1, v2
	v_lshlrev_b32_e32 v2, 14, v13
	v_and_b32_e32 v2, 0xffff8000, v2
	s_waitcnt vmcnt(6)
	v_lshl_add_u32 v2, v14, 11, v2
	v_and_b32_e32 v3, 1, v13
	v_lshl_or_b32 v2, v3, 6, v2
	s_cselect_b64 s[14:15], -1, 0
	v_or_b32_e32 v146, s22, v18
	v_mov_b32_e32 v137, v1
	v_lshl_add_u32 v138, v15, 1, v2
	v_mov_b32_e32 v139, v1
	s_mov_b32 s52, 0
	v_add_u32_e32 v147, 0, v17
	s_barrier
	s_mov_b32 s100, 0x10000
	s_cmp_eq_u32 s65, 0
	s_cbranch_scc1 .Lslot_done
	s_cmpk_lg_u32 s33, 0x100
	s_cbranch_scc1 .Lslot_done
	s_load_dwordx2 s[98:99], s[0:1], 0x128
	s_and_b32 s101, s8, 7
	s_lshl_b32 s101, s101, 8
	s_waitcnt lgkmcnt(0)
	s_add_u32 s98, s98, s101
	s_addc_u32 s99, s99, 0
	s_add_u32 s98, s98, 0x302400
	s_addc_u32 s99, s99, 0
	global_load_dword v2, v1, s[98:99] sc1
	s_waitcnt vmcnt(0)
	v_readfirstlane_b32 s101, v2
	s_nop 3
	s_cmp_lt_u32 s101, 6
	s_cbranch_scc0 .Lslot_done
	s_lshr_b32 s98, s8, 3
	s_cmp_lt_u32 s98, 16
	s_cbranch_scc0 .Lslot_done
	s_lshl_b32 s101, s101, 4
	s_add_i32 s100, s98, s101
